# P5->P6 hand-off through per-row-block flags (baseline's own release/acquire protocol: sc1 Act stores, deferred signal at the next drain point, bounded poll of >=22 tiles) instead of the last grid barr
# speedup vs baseline: 1.0167x; 1.0167x over previous
_Z14fwd_megakernel6Params:
	s_load_dwordx16 s[52:67], s[0:1], 0x0
	s_load_dwordx16 s[12:27], s[0:1], 0x40
	s_load_dwordx16 s[36:51], s[0:1], 0xc0
	s_load_dwordx4 s[28:31], s[0:1], 0x178
	s_load_dwordx8 s[88:95], s[0:1], 0x158
	s_cmp_eq_u32 s2, 0
	s_mov_b64 s[96:97], s[0:1]
	s_mov_b32 s10, s2
	s_waitcnt lgkmcnt(0)
	v_writelane_b32 v249, s12, 0
	s_nop 1
	v_writelane_b32 v249, s13, 1
	v_writelane_b32 v249, s14, 2
	v_writelane_b32 v249, s15, 3
	v_writelane_b32 v249, s16, 4
	v_writelane_b32 v249, s17, 5
	v_writelane_b32 v249, s18, 6
	v_writelane_b32 v249, s19, 7
	v_writelane_b32 v249, s20, 8
	v_writelane_b32 v249, s21, 9
	v_writelane_b32 v249, s22, 10
	v_writelane_b32 v249, s23, 11
	v_writelane_b32 v249, s24, 12
	v_writelane_b32 v249, s25, 13
	v_writelane_b32 v249, s26, 14
	v_writelane_b32 v249, s27, 15
	s_load_dwordx16 s[12:27], s[0:1], 0x80
	s_cselect_b64 s[0:1], -1, 0
	s_cmp_lg_u32 s2, 0
	s_waitcnt lgkmcnt(0)
	v_writelane_b32 v249, s12, 16
	s_nop 1
	v_writelane_b32 v249, s13, 17
	v_writelane_b32 v249, s14, 18
	v_writelane_b32 v249, s15, 19
	v_writelane_b32 v249, s16, 20
	v_writelane_b32 v249, s17, 21
	v_writelane_b32 v249, s18, 22
	v_writelane_b32 v249, s19, 23
	v_writelane_b32 v249, s20, 24
	v_writelane_b32 v249, s21, 25
	v_writelane_b32 v249, s22, 26
	v_writelane_b32 v249, s23, 27
	v_writelane_b32 v249, s24, 28
	v_writelane_b32 v249, s25, 29
	v_writelane_b32 v249, s26, 30
	v_writelane_b32 v249, s27, 31
	v_writelane_b32 v249, s0, 32
	s_nop 1
	v_writelane_b32 v249, s1, 33
	s_cbranch_scc1 .LBB0_4
	s_movk_i32 s0, 0xc0
	v_cmp_gt_u32_e32 vcc, s0, v0
	s_and_saveexec_b64 s[2:3], vcc
	s_cbranch_execz .LBB0_3
	v_lshlrev_b32_e32 v1, 6, v0
	v_and_b32_e32 v2, 0x3000, v1
	v_mov_b32_e32 v3, 0
	v_lshl_add_u64 v[4:5], s[94:95], 0, v[2:3]
	v_and_b32_e32 v2, 0xfc0, v1
	v_lshl_add_u64 v[4:5], v[4:5], 0, v[2:3]
	v_add_co_u32_e32 v4, vcc, 0x1000, v4
	s_nop 1
	v_addc_co_u32_e32 v5, vcc, 0, v5, vcc
	global_atomic_swap v[4:5], v3, off

.LBB0_337:
	s_mov_b32 s99, -1
	s_cmp_lt_i32 s84, 7
	s_cselect_b64 s[8:9], -1, 0
	s_cmp_gt_i32 s86, 5
	s_cselect_b64 s[0:1], -1, 0
	s_and_b64 s[0:1], s[8:9], s[0:1]
	s_andn2_b64 vcc, exec, s[0:1]
	s_cbranch_vccnz .LBB0_371
	s_cmpk_gt_i32 s10, 0x57f
	s_cbranch_scc1 .LBB0_371
	v_lshlrev_b32_e32 v6, 6, v0
	s_movk_i32 s0, 0x100
	v_lshlrev_b32_e32 v3, 2, v0
	v_and_b32_e32 v5, 48, v0
	v_and_b32_e32 v7, 0x3c0, v6
	v_cmp_gt_u32_e64 s[4:5], s0, v0
	v_or_b32_e32 v1, 0x20000, v3
	v_or_b32_e32 v8, v7, v5
	v_and_b32_e32 v3, 32, v3
	s_mov_b32 s0, 0x10000
	v_bitop3_b32 v5, v7, v3, v5 bitop3:0x36
	v_bitop3_b32 v7, v8, s0, v3 bitop3:0xde
	s_mov_b32 s0, 0x14000
	v_bitop3_b32 v9, v8, s0, v3 bitop3:0xde
	s_mov_b32 s0, 0x18000
	s_add_u32 s11, s94, 0x2000
	v_lshrrev_b32_e32 v4, 8, v0
	v_bitop3_b32 v10, v8, s0, v3 bitop3:0xde
	s_mov_b32 s0, 0x1c000
	v_and_b32_e32 v2, 15, v0
	s_addc_u32 s33, s95, 0
	v_cmp_eq_u32_e64 s[6:7], 1, v4
	v_bitop3_b32 v3, v8, s0, v3 bitop3:0xde
	v_lshlrev_b32_e32 v4, 13, v4
	v_lshrrev_b32_e32 v13, 1, v0
	s_movk_i32 s0, 0x60
	v_and_b32_e32 v6, 0x3000, v6
	v_or_b32_e32 v8, 0x800, v4
	v_or_b32_e32 v11, 0x1000, v4
	v_or_b32_e32 v12, 0x1800, v4
	s_add_u32 s16, s96, 0x188
	v_and_or_b32 v142, v13, s0, v2
	v_lshrrev_b32_e32 v2, 2, v0
	v_cmp_eq_u32_e64 s[2:3], 0, v0
	s_addc_u32 s17, s97, 0
	v_and_b32_e32 v143, 0x4c, v2
	v_mov_b32_e32 v131, 0
	v_mov_b32_e32 v144, 0x358637bd
	s_mov_b32 s52, 0x800000
	s_mov_b64 s[18:19], 0x80
	s_mov_b64 s[20:21], 0x40080
	v_add_u32_e32 v145, v7, v6
	v_add_u32_e32 v146, v5, v4
	v_add_u32_e32 v147, v5, v8
	v_add_u32_e32 v148, v5, v11
	v_add_u32_e32 v149, v5, v12
	v_add_u32_e32 v150, v9, v6
	s_mov_b64 s[22:23], 0x100
	s_mov_b64 s[26:27], 0x40100
	v_add_u32_e32 v151, v10, v6
	v_add_u32_e32 v152, v3, v6
	s_mov_b64 s[28:29], 0x180
	s_mov_b64 s[30:31], 0x40180
	s_movk_i32 s53, 0x1600
	v_mov_b32_e32 v153, 1
	v_mov_b32_e32 v154, 0x20000
	s_mov_b32 s54, s10
	s_branch .LBB0_342

.LBB0_341:
	s_or_b64 exec, exec, s[40:41]
	v_mbcnt_lo_u32_b32 v244, -1, 0
	v_mbcnt_hi_u32_b32 v244, -1, v244
	v_bfe_u32 v244, v244, 4, 1
	v_mul_u32_u24_e32 v244, 24, v244
	v_mov_b32_e32 v245, 0
	v_lshl_or_b32 v132, s36, 7, v143
	v_mov_b32_e32 v130, v142
	s_andn2_b64 vcc, exec, s[38:39]
	v_lshl_add_u32 v140, v130, 2, v154
	ds_read2_b32 v[134:135], v140 offset1:16
	v_ashrrev_i32_e32 v133, 31, v132
	v_lshl_add_u32 v130, s34, 8, v130
	s_waitcnt lgkmcnt(0)
	v_pk_mul_f32 v[122:123], v[122:123], v[134:135] op_sel_hi:[1,0]
	s_nop 0
	v_mul_f32_e32 v136, 0xbfb8aa3b, v122
	v_mul_f32_e32 v137, 0xbfb8aa3b, v123
	v_pk_mul_f32 v[124:125], v[124:125], v[134:135] op_sel_hi:[1,0]
	v_exp_f32_e32 v136, v136
	v_exp_f32_e32 v137, v137
	v_mul_f32_e32 v138, 0xbfb8aa3b, v124
	v_mul_f32_e32 v139, 0xbfb8aa3b, v125
	v_exp_f32_e32 v138, v138
	v_exp_f32_e32 v139, v139
	v_add_f32_e32 v136, 1.0, v136
	v_add_f32_e32 v137, 1.0, v137
	v_rcp_f32_e32 v136, v136
	v_rcp_f32_e32 v137, v137
	v_add_f32_e32 v138, 1.0, v138
	v_add_f32_e32 v139, 1.0, v139
	v_rcp_f32_e32 v138, v138
	v_rcp_f32_e32 v139, v139
	v_pk_mul_f32 v[122:123], v[122:123], v[136:137]
	v_pk_mul_f32 v[126:127], v[126:127], v[134:135] op_sel_hi:[1,0]
	v_pk_mul_f32 v[114:115], v[114:115], v[134:135] op_sel_hi:[1,0]
	v_pk_mul_f32 v[122:123], v[126:127], v[122:123]
	v_pk_mul_f32 v[124:125], v[124:125], v[138:139]
	v_pk_mul_f32 v[126:127], v[128:129], v[134:135] op_sel_hi:[1,0]
	v_pk_mul_f32 v[116:117], v[116:117], v[134:135] op_sel_hi:[1,0]
	v_pk_mul_f32 v[124:125], v[126:127], v[124:125]
	v_cvt_pk_bf16_f32 v224, v122, v123
	v_cvt_pk_bf16_f32 v225, v124, v125
	v_lshlrev_b64 v[124:125], 1, v[132:133]
	v_mul_f32_e32 v132, 0xbfb8aa3b, v114
	v_mul_f32_e32 v133, 0xbfb8aa3b, v115
	v_exp_f32_e32 v132, v132
	v_exp_f32_e32 v133, v133
	v_mov_b64_e32 v[122:123], s[14:15]
	v_mad_i64_i32 v[128:129], s[0:1], v130, s53, v[122:123]
	v_lshl_add_u64 v[128:129], v[128:129], 0, v[124:125]
	v_add_f32_e32 v126, 1.0, v132
	v_add_f32_e32 v127, 1.0, v133
	v_mul_f32_e32 v132, 0xbfb8aa3b, v116
	v_mul_f32_e32 v133, 0xbfb8aa3b, v117
	v_exp_f32_e32 v132, v132
	v_exp_f32_e32 v133, v133
	v_rcp_f32_e32 v126, v126
	v_rcp_f32_e32 v127, v127
	v_add_f32_e32 v132, 1.0, v132
	v_add_f32_e32 v133, 1.0, v133
	v_rcp_f32_e32 v132, v132
	v_rcp_f32_e32 v133, v133
	v_pk_mul_f32 v[114:115], v[114:115], v[126:127]
	v_pk_mul_f32 v[118:119], v[118:119], v[134:135] op_sel_hi:[1,0]
	v_pk_mul_f32 v[106:107], v[106:107], v[134:135] op_sel_hi:[1,0]
	v_pk_mul_f32 v[114:115], v[118:119], v[114:115]
	v_pk_mul_f32 v[116:117], v[116:117], v[132:133]
	v_pk_mul_f32 v[118:119], v[120:121], v[134:135] op_sel_hi:[1,0]
	v_cvt_pk_bf16_f32 v226, v114, v115
	v_pk_mul_f32 v[116:117], v[118:119], v[116:117]
	v_pk_mul_f32 v[108:109], v[108:109], v[134:135] op_sel_hi:[1,0]
	v_cvt_pk_bf16_f32 v227, v116, v117
	v_mul_f32_e32 v116, 0xbfb8aa3b, v106
	v_mul_f32_e32 v117, 0xbfb8aa3b, v107
	v_exp_f32_e32 v116, v116
	v_exp_f32_e32 v117, v117
	v_pk_mul_f32 v[110:111], v[110:111], v[134:135] op_sel_hi:[1,0]
	v_add_f32_e32 v114, 1.0, v116
	v_add_f32_e32 v115, 1.0, v117
	v_mul_f32_e32 v116, 0xbfb8aa3b, v108
	v_mul_f32_e32 v117, 0xbfb8aa3b, v109
	v_exp_f32_e32 v116, v116
	v_exp_f32_e32 v117, v117
	v_rcp_f32_e32 v114, v114
	v_rcp_f32_e32 v115, v115
	v_add_f32_e32 v116, 1.0, v116
	v_add_f32_e32 v117, 1.0, v117
	v_rcp_f32_e32 v116, v116
	v_rcp_f32_e32 v117, v117
	v_pk_mul_f32 v[106:107], v[106:107], v[114:115]
	v_pk_mul_f32 v[98:99], v[98:99], v[134:135] op_sel_hi:[1,0]
	v_pk_mul_f32 v[106:107], v[110:111], v[106:107]
	v_pk_mul_f32 v[108:109], v[108:109], v[116:117]
	v_pk_mul_f32 v[110:111], v[112:113], v[134:135] op_sel_hi:[1,0]
	v_cvt_pk_bf16_f32 v228, v106, v107
	v_pk_mul_f32 v[108:109], v[110:111], v[108:109]
	v_pk_mul_f32 v[100:101], v[100:101], v[134:135] op_sel_hi:[1,0]
	v_cvt_pk_bf16_f32 v229, v108, v109
	v_mul_f32_e32 v108, 0xbfb8aa3b, v98
	v_mul_f32_e32 v109, 0xbfb8aa3b, v99
	v_exp_f32_e32 v108, v108
	v_exp_f32_e32 v109, v109
	v_pk_mul_f32 v[102:103], v[102:103], v[134:135] op_sel_hi:[1,0]
	v_add_f32_e32 v106, 1.0, v108
	v_add_f32_e32 v107, 1.0, v109
	v_mul_f32_e32 v108, 0xbfb8aa3b, v100
	v_mul_f32_e32 v109, 0xbfb8aa3b, v101
	v_exp_f32_e32 v108, v108
	v_exp_f32_e32 v109, v109
	v_rcp_f32_e32 v106, v106
	v_rcp_f32_e32 v107, v107
	v_add_f32_e32 v108, 1.0, v108
	v_add_f32_e32 v109, 1.0, v109
	v_rcp_f32_e32 v108, v108
	v_rcp_f32_e32 v109, v109
	v_pk_mul_f32 v[98:99], v[98:99], v[106:107]
	v_pk_mul_f32 v[100:101], v[100:101], v[108:109]
	v_pk_mul_f32 v[98:99], v[102:103], v[98:99]
	v_pk_mul_f32 v[102:103], v[104:105], v[134:135] op_sel_hi:[1,0]
	v_cvt_pk_bf16_f32 v230, v98, v99
	v_pk_mul_f32 v[100:101], v[102:103], v[100:101]
	v_add_u32_e32 v104, 16, v130
	v_cvt_pk_bf16_f32 v231, v100, v101
	s_nop 1
	v_permlane16_swap_b32_e32 v224, v226
	v_permlane16_swap_b32_e32 v225, v227
	v_permlane16_swap_b32_e32 v228, v230
	v_permlane16_swap_b32_e32 v229, v231
	v_lshl_add_u64 v[240:241], v[128:129], 0, v[244:245]
	global_store_dwordx4 v[240:241], v[224:227], off sc1
	global_store_dwordx4 v[240:241], v[228:231], off offset:64 sc1
	v_mov_b32_e32 v98, v135
	v_pk_mul_f32 v[90:91], v[90:91], v[98:99] op_sel_hi:[1,0]
	s_nop 0
	v_mul_f32_e32 v99, 0xbfb8aa3b, v90
	v_exp_f32_e32 v99, v99
	v_mul_f32_e32 v100, 0xbfb8aa3b, v91
	v_exp_f32_e32 v101, v100
	v_add_f32_e32 v99, 1.0, v99
	v_rcp_f32_e32 v100, v99
	v_add_f32_e32 v99, 1.0, v101
	v_pk_mul_f32 v[92:93], v[92:93], v[98:99] op_sel_hi:[1,0]
	s_nop 0
	v_mul_f32_e32 v101, 0xbfb8aa3b, v92
	v_exp_f32_e32 v102, v101
	v_mul_f32_e32 v101, 0xbfb8aa3b, v93
	v_exp_f32_e32 v103, v101
	v_rcp_f32_e32 v101, v99
	v_add_f32_e32 v99, 1.0, v102
	v_rcp_f32_e32 v102, v99
	v_add_f32_e32 v99, 1.0, v103
	v_rcp_f32_e32 v103, v99
	v_pk_mul_f32 v[90:91], v[90:91], v[100:101]
	v_pk_mul_f32 v[94:95], v[94:95], v[98:99] op_sel_hi:[1,0]
	v_pk_mul_f32 v[82:83], v[82:83], v[98:99] op_sel_hi:[1,0]
	v_pk_mul_f32 v[90:91], v[94:95], v[90:91]
	v_pk_mul_f32 v[92:93], v[92:93], v[102:103]
	v_pk_mul_f32 v[94:95], v[96:97], v[98:99] op_sel_hi:[1,0]
	v_cvt_pk_bf16_f32 v232, v90, v91
	v_pk_mul_f32 v[92:93], v[94:95], v[92:93]
	v_mul_f32_e32 v94, 0xbfb8aa3b, v82
	v_mul_f32_e32 v95, 0xbfb8aa3b, v83
	v_exp_f32_e32 v94, v94
	v_exp_f32_e32 v95, v95
	v_cvt_pk_bf16_f32 v233, v92, v93
	v_mad_i64_i32 v[92:93], s[0:1], v104, s53, v[122:123]
	v_lshl_add_u64 v[92:93], v[92:93], 0, v[124:125]
	v_pk_mul_f32 v[84:85], v[84:85], v[98:99] op_sel_hi:[1,0]
	v_add_f32_e32 v90, 1.0, v94
	v_add_f32_e32 v91, 1.0, v95
	v_mul_f32_e32 v94, 0xbfb8aa3b, v84
	v_mul_f32_e32 v95, 0xbfb8aa3b, v85
	v_exp_f32_e32 v94, v94
	v_exp_f32_e32 v95, v95
	v_rcp_f32_e32 v90, v90
	v_rcp_f32_e32 v91, v91
	v_add_f32_e32 v94, 1.0, v94
	v_add_f32_e32 v95, 1.0, v95
	v_rcp_f32_e32 v94, v94
	v_rcp_f32_e32 v95, v95
	v_pk_mul_f32 v[82:83], v[82:83], v[90:91]
	v_pk_mul_f32 v[86:87], v[86:87], v[98:99] op_sel_hi:[1,0]
	v_pk_mul_f32 v[74:75], v[74:75], v[98:99] op_sel_hi:[1,0]
	v_pk_mul_f32 v[82:83], v[86:87], v[82:83]
	v_pk_mul_f32 v[84:85], v[84:85], v[94:95]
	v_pk_mul_f32 v[86:87], v[88:89], v[98:99] op_sel_hi:[1,0]
	v_cvt_pk_bf16_f32 v234, v82, v83
	v_pk_mul_f32 v[84:85], v[86:87], v[84:85]
	v_pk_mul_f32 v[76:77], v[76:77], v[98:99] op_sel_hi:[1,0]
	v_cvt_pk_bf16_f32 v235, v84, v85
	v_mul_f32_e32 v84, 0xbfb8aa3b, v74
	v_mul_f32_e32 v85, 0xbfb8aa3b, v75
	v_exp_f32_e32 v84, v84
	v_exp_f32_e32 v85, v85
	v_pk_mul_f32 v[78:79], v[78:79], v[98:99] op_sel_hi:[1,0]
	v_add_f32_e32 v82, 1.0, v84
	v_add_f32_e32 v83, 1.0, v85
	v_mul_f32_e32 v84, 0xbfb8aa3b, v76
	v_mul_f32_e32 v85, 0xbfb8aa3b, v77
	v_exp_f32_e32 v84, v84
	v_exp_f32_e32 v85, v85
	v_rcp_f32_e32 v82, v82
	v_rcp_f32_e32 v83, v83
	v_add_f32_e32 v84, 1.0, v84
	v_add_f32_e32 v85, 1.0, v85
	v_rcp_f32_e32 v84, v84
	v_rcp_f32_e32 v85, v85
	v_pk_mul_f32 v[74:75], v[74:75], v[82:83]
	v_pk_mul_f32 v[66:67], v[66:67], v[98:99] op_sel_hi:[1,0]
	v_pk_mul_f32 v[74:75], v[78:79], v[74:75]
	v_pk_mul_f32 v[76:77], v[76:77], v[84:85]
	v_pk_mul_f32 v[78:79], v[80:81], v[98:99] op_sel_hi:[1,0]
	v_cvt_pk_bf16_f32 v236, v74, v75
	v_pk_mul_f32 v[76:77], v[78:79], v[76:77]
	v_pk_mul_f32 v[68:69], v[68:69], v[98:99] op_sel_hi:[1,0]
	v_cvt_pk_bf16_f32 v237, v76, v77
	v_mul_f32_e32 v76, 0xbfb8aa3b, v66
	v_mul_f32_e32 v77, 0xbfb8aa3b, v67
	v_exp_f32_e32 v76, v76
	v_exp_f32_e32 v77, v77
	v_pk_mul_f32 v[70:71], v[70:71], v[98:99] op_sel_hi:[1,0]
	v_add_f32_e32 v74, 1.0, v76
	v_add_f32_e32 v75, 1.0, v77
	v_mul_f32_e32 v76, 0xbfb8aa3b, v68
	v_mul_f32_e32 v77, 0xbfb8aa3b, v69
	v_exp_f32_e32 v76, v76
	v_exp_f32_e32 v77, v77
	v_rcp_f32_e32 v74, v74
	v_rcp_f32_e32 v75, v75
	v_add_f32_e32 v76, 1.0, v76
	v_add_f32_e32 v77, 1.0, v77
	v_rcp_f32_e32 v76, v76
	v_rcp_f32_e32 v77, v77
	v_pk_mul_f32 v[66:67], v[66:67], v[74:75]
	v_pk_mul_f32 v[68:69], v[68:69], v[76:77]
	v_pk_mul_f32 v[66:67], v[70:71], v[66:67]
	v_pk_mul_f32 v[70:71], v[72:73], v[98:99] op_sel_hi:[1,0]
	ds_read2_b32 v[72:73], v140 offset0:128 offset1:144
	v_pk_mul_f32 v[68:69], v[70:71], v[68:69]
	v_cvt_pk_bf16_f32 v238, v66, v67
	v_cvt_pk_bf16_f32 v239, v68, v69
	s_nop 1
	v_permlane16_swap_b32_e32 v232, v234
	v_permlane16_swap_b32_e32 v233, v235
	v_permlane16_swap_b32_e32 v236, v238
	v_permlane16_swap_b32_e32 v237, v239
	v_lshl_add_u64 v[240:241], v[92:93], 0, v[244:245]
	global_store_dwordx4 v[240:241], v[232:235], off sc1
	global_store_dwordx4 v[240:241], v[236:239], off offset:64 sc1
	s_waitcnt lgkmcnt(0)
	v_pk_mul_f32 v[58:59], v[58:59], v[72:73] op_sel_hi:[1,0]
	v_pk_mul_f32 v[60:61], v[60:61], v[72:73] op_sel_hi:[1,0]
	v_mul_f32_e32 v66, 0xbfb8aa3b, v58
	v_mul_f32_e32 v67, 0xbfb8aa3b, v59
	v_exp_f32_e32 v66, v66
	v_exp_f32_e32 v67, v67
	v_mul_f32_e32 v68, 0xbfb8aa3b, v60
	v_mul_f32_e32 v69, 0xbfb8aa3b, v61
	v_exp_f32_e32 v68, v68
	v_exp_f32_e32 v69, v69
	v_add_f32_e32 v66, 1.0, v66
	v_add_f32_e32 v67, 1.0, v67
	v_rcp_f32_e32 v66, v66
	v_rcp_f32_e32 v67, v67
	v_add_f32_e32 v68, 1.0, v68
	v_add_f32_e32 v69, 1.0, v69
	v_rcp_f32_e32 v68, v68
	v_rcp_f32_e32 v69, v69
	v_pk_mul_f32 v[58:59], v[58:59], v[66:67]
	v_pk_mul_f32 v[62:63], v[62:63], v[72:73] op_sel_hi:[1,0]
	v_pk_mul_f32 v[50:51], v[50:51], v[72:73] op_sel_hi:[1,0]
	v_pk_mul_f32 v[58:59], v[62:63], v[58:59]
	v_pk_mul_f32 v[60:61], v[60:61], v[68:69]
	v_pk_mul_f32 v[62:63], v[64:65], v[72:73] op_sel_hi:[1,0]
	v_add_u32_e32 v70, 0x80, v130
	v_pk_mul_f32 v[60:61], v[62:63], v[60:61]
	v_mul_f32_e32 v62, 0xbfb8aa3b, v50
	v_mul_f32_e32 v63, 0xbfb8aa3b, v51
	v_exp_f32_e32 v62, v62
	v_exp_f32_e32 v63, v63
	v_cvt_pk_bf16_f32 v224, v58, v59
	v_cvt_pk_bf16_f32 v225, v60, v61
	v_mad_i64_i32 v[60:61], s[0:1], v70, s53, v[122:123]
	v_lshl_add_u64 v[60:61], v[60:61], 0, v[124:125]
	v_pk_mul_f32 v[52:53], v[52:53], v[72:73] op_sel_hi:[1,0]
	v_add_f32_e32 v58, 1.0, v62
	v_add_f32_e32 v59, 1.0, v63
	v_mul_f32_e32 v62, 0xbfb8aa3b, v52
	v_mul_f32_e32 v63, 0xbfb8aa3b, v53
	v_exp_f32_e32 v62, v62
	v_exp_f32_e32 v63, v63
	v_rcp_f32_e32 v58, v58
	v_rcp_f32_e32 v59, v59
	v_add_f32_e32 v62, 1.0, v62
	v_add_f32_e32 v63, 1.0, v63
	v_rcp_f32_e32 v62, v62
	v_rcp_f32_e32 v63, v63
	v_pk_mul_f32 v[50:51], v[50:51], v[58:59]
	v_pk_mul_f32 v[54:55], v[54:55], v[72:73] op_sel_hi:[1,0]
	v_pk_mul_f32 v[42:43], v[42:43], v[72:73] op_sel_hi:[1,0]
	v_pk_mul_f32 v[50:51], v[54:55], v[50:51]
	v_pk_mul_f32 v[52:53], v[52:53], v[62:63]
	v_pk_mul_f32 v[54:55], v[56:57], v[72:73] op_sel_hi:[1,0]
	v_cvt_pk_bf16_f32 v226, v50, v51
	v_pk_mul_f32 v[52:53], v[54:55], v[52:53]
	v_pk_mul_f32 v[44:45], v[44:45], v[72:73] op_sel_hi:[1,0]
	v_cvt_pk_bf16_f32 v227, v52, v53
	v_mul_f32_e32 v52, 0xbfb8aa3b, v42
	v_mul_f32_e32 v53, 0xbfb8aa3b, v43
	v_exp_f32_e32 v52, v52
	v_exp_f32_e32 v53, v53
	v_pk_mul_f32 v[46:47], v[46:47], v[72:73] op_sel_hi:[1,0]
	v_add_f32_e32 v50, 1.0, v52
	v_add_f32_e32 v51, 1.0, v53
	v_mul_f32_e32 v52, 0xbfb8aa3b, v44
	v_mul_f32_e32 v53, 0xbfb8aa3b, v45
	v_exp_f32_e32 v52, v52
	v_exp_f32_e32 v53, v53
	v_rcp_f32_e32 v50, v50
	v_rcp_f32_e32 v51, v51
	v_add_f32_e32 v52, 1.0, v52
	v_add_f32_e32 v53, 1.0, v53
	v_rcp_f32_e32 v52, v52
	v_rcp_f32_e32 v53, v53
	v_pk_mul_f32 v[42:43], v[42:43], v[50:51]
	v_pk_mul_f32 v[34:35], v[34:35], v[72:73] op_sel_hi:[1,0]
	v_pk_mul_f32 v[42:43], v[46:47], v[42:43]
	v_pk_mul_f32 v[44:45], v[44:45], v[52:53]
	v_pk_mul_f32 v[46:47], v[48:49], v[72:73] op_sel_hi:[1,0]
	v_cvt_pk_bf16_f32 v228, v42, v43
	v_pk_mul_f32 v[44:45], v[46:47], v[44:45]
	v_pk_mul_f32 v[36:37], v[36:37], v[72:73] op_sel_hi:[1,0]
	v_cvt_pk_bf16_f32 v229, v44, v45
	v_mul_f32_e32 v44, 0xbfb8aa3b, v34
	v_mul_f32_e32 v45, 0xbfb8aa3b, v35
	v_exp_f32_e32 v44, v44
	v_exp_f32_e32 v45, v45
	v_pk_mul_f32 v[38:39], v[38:39], v[72:73] op_sel_hi:[1,0]
	v_add_f32_e32 v42, 1.0, v44
	v_add_f32_e32 v43, 1.0, v45
	v_mul_f32_e32 v44, 0xbfb8aa3b, v36
	v_mul_f32_e32 v45, 0xbfb8aa3b, v37
	v_exp_f32_e32 v44, v44
	v_exp_f32_e32 v45, v45
	v_rcp_f32_e32 v42, v42
	v_rcp_f32_e32 v43, v43
	v_add_f32_e32 v44, 1.0, v44
	v_add_f32_e32 v45, 1.0, v45
	v_rcp_f32_e32 v44, v44
	v_rcp_f32_e32 v45, v45
	v_pk_mul_f32 v[34:35], v[34:35], v[42:43]
	v_pk_mul_f32 v[36:37], v[36:37], v[44:45]
	v_pk_mul_f32 v[34:35], v[38:39], v[34:35]
	v_pk_mul_f32 v[38:39], v[40:41], v[72:73] op_sel_hi:[1,0]
	v_cvt_pk_bf16_f32 v230, v34, v35
	v_pk_mul_f32 v[36:37], v[38:39], v[36:37]
	v_add_u32_e32 v40, 0x90, v130
	v_cvt_pk_bf16_f32 v231, v36, v37
	s_nop 1
	v_permlane16_swap_b32_e32 v224, v226
	v_permlane16_swap_b32_e32 v225, v227
	v_permlane16_swap_b32_e32 v228, v230
	v_permlane16_swap_b32_e32 v229, v231
	v_lshl_add_u64 v[240:241], v[60:61], 0, v[244:245]
	global_store_dwordx4 v[240:241], v[224:227], off sc1
	global_store_dwordx4 v[240:241], v[228:231], off offset:64 sc1
	v_mov_b32_e32 v34, v73
	v_pk_mul_f32 v[26:27], v[26:27], v[34:35] op_sel_hi:[1,0]
	s_nop 0
	v_mul_f32_e32 v35, 0xbfb8aa3b, v26
	v_exp_f32_e32 v35, v35
	v_mul_f32_e32 v36, 0xbfb8aa3b, v27
	v_exp_f32_e32 v37, v36
	v_add_f32_e32 v35, 1.0, v35
	v_rcp_f32_e32 v36, v35
	v_add_f32_e32 v35, 1.0, v37
	v_pk_mul_f32 v[28:29], v[28:29], v[34:35] op_sel_hi:[1,0]
	s_nop 0
	v_mul_f32_e32 v37, 0xbfb8aa3b, v28
	v_exp_f32_e32 v38, v37
	v_mul_f32_e32 v37, 0xbfb8aa3b, v29
	v_exp_f32_e32 v39, v37
	v_rcp_f32_e32 v37, v35
	v_add_f32_e32 v35, 1.0, v38
	v_rcp_f32_e32 v38, v35
	v_add_f32_e32 v35, 1.0, v39
	v_rcp_f32_e32 v39, v35
	v_pk_mul_f32 v[26:27], v[26:27], v[36:37]
	v_pk_mul_f32 v[30:31], v[30:31], v[34:35] op_sel_hi:[1,0]
	v_pk_mul_f32 v[18:19], v[18:19], v[34:35] op_sel_hi:[1,0]
	v_pk_mul_f32 v[26:27], v[30:31], v[26:27]
	v_pk_mul_f32 v[28:29], v[28:29], v[38:39]
	v_pk_mul_f32 v[30:31], v[32:33], v[34:35] op_sel_hi:[1,0]
	v_cvt_pk_bf16_f32 v232, v26, v27
	v_pk_mul_f32 v[28:29], v[30:31], v[28:29]
	v_mul_f32_e32 v30, 0xbfb8aa3b, v18
	v_mul_f32_e32 v31, 0xbfb8aa3b, v19
	v_exp_f32_e32 v30, v30
	v_exp_f32_e32 v31, v31
	v_cvt_pk_bf16_f32 v233, v28, v29
	v_mad_i64_i32 v[28:29], s[0:1], v40, s53, v[122:123]
	v_lshl_add_u64 v[28:29], v[28:29], 0, v[124:125]
	v_pk_mul_f32 v[20:21], v[20:21], v[34:35] op_sel_hi:[1,0]
	v_add_f32_e32 v26, 1.0, v30
	v_add_f32_e32 v27, 1.0, v31
	v_mul_f32_e32 v30, 0xbfb8aa3b, v20
	v_mul_f32_e32 v31, 0xbfb8aa3b, v21
	v_exp_f32_e32 v30, v30
	v_exp_f32_e32 v31, v31
	v_rcp_f32_e32 v26, v26
	v_rcp_f32_e32 v27, v27
	v_add_f32_e32 v30, 1.0, v30
	v_add_f32_e32 v31, 1.0, v31
	v_rcp_f32_e32 v30, v30
	v_rcp_f32_e32 v31, v31
	v_pk_mul_f32 v[18:19], v[18:19], v[26:27]
	v_pk_mul_f32 v[22:23], v[22:23], v[34:35] op_sel_hi:[1,0]
	v_pk_mul_f32 v[10:11], v[10:11], v[34:35] op_sel_hi:[1,0]
	v_pk_mul_f32 v[18:19], v[22:23], v[18:19]
	v_pk_mul_f32 v[20:21], v[20:21], v[30:31]
	v_pk_mul_f32 v[22:23], v[24:25], v[34:35] op_sel_hi:[1,0]
	v_cvt_pk_bf16_f32 v234, v18, v19
	v_pk_mul_f32 v[20:21], v[22:23], v[20:21]
	v_pk_mul_f32 v[12:13], v[12:13], v[34:35] op_sel_hi:[1,0]
	v_cvt_pk_bf16_f32 v235, v20, v21
	v_mul_f32_e32 v20, 0xbfb8aa3b, v10
	v_mul_f32_e32 v21, 0xbfb8aa3b, v11
	v_exp_f32_e32 v20, v20
	v_exp_f32_e32 v21, v21
	v_pk_mul_f32 v[14:15], v[14:15], v[34:35] op_sel_hi:[1,0]
	v_add_f32_e32 v18, 1.0, v20
	v_add_f32_e32 v19, 1.0, v21
	v_mul_f32_e32 v20, 0xbfb8aa3b, v12
	v_mul_f32_e32 v21, 0xbfb8aa3b, v13
	v_exp_f32_e32 v20, v20
	v_exp_f32_e32 v21, v21
	v_rcp_f32_e32 v18, v18
	v_rcp_f32_e32 v19, v19
	v_add_f32_e32 v20, 1.0, v20
	v_add_f32_e32 v21, 1.0, v21
	v_rcp_f32_e32 v20, v20
	v_rcp_f32_e32 v21, v21
	v_pk_mul_f32 v[10:11], v[10:11], v[18:19]
	v_pk_mul_f32 v[2:3], v[2:3], v[34:35] op_sel_hi:[1,0]
	v_pk_mul_f32 v[10:11], v[14:15], v[10:11]
	v_pk_mul_f32 v[12:13], v[12:13], v[20:21]
	v_pk_mul_f32 v[14:15], v[16:17], v[34:35] op_sel_hi:[1,0]
	v_cvt_pk_bf16_f32 v236, v10, v11
	v_pk_mul_f32 v[12:13], v[14:15], v[12:13]
	v_pk_mul_f32 v[4:5], v[4:5], v[34:35] op_sel_hi:[1,0]
	v_cvt_pk_bf16_f32 v237, v12, v13
	v_mul_f32_e32 v12, 0xbfb8aa3b, v2
	v_mul_f32_e32 v13, 0xbfb8aa3b, v3
	v_exp_f32_e32 v12, v12
	v_exp_f32_e32 v13, v13
	v_pk_mul_f32 v[6:7], v[6:7], v[34:35] op_sel_hi:[1,0]
	v_add_f32_e32 v10, 1.0, v12
	v_add_f32_e32 v11, 1.0, v13
	v_mul_f32_e32 v12, 0xbfb8aa3b, v4
	v_mul_f32_e32 v13, 0xbfb8aa3b, v5
	v_exp_f32_e32 v12, v12
	v_exp_f32_e32 v13, v13
	v_rcp_f32_e32 v10, v10
	v_rcp_f32_e32 v11, v11
	v_add_f32_e32 v12, 1.0, v12
	v_add_f32_e32 v13, 1.0, v13
	v_rcp_f32_e32 v12, v12
	v_rcp_f32_e32 v13, v13
	v_pk_mul_f32 v[2:3], v[2:3], v[10:11]
	v_pk_mul_f32 v[4:5], v[4:5], v[12:13]
	v_pk_mul_f32 v[2:3], v[6:7], v[2:3]
	v_pk_mul_f32 v[6:7], v[8:9], v[34:35] op_sel_hi:[1,0]
	v_cvt_pk_bf16_f32 v238, v2, v3
	v_pk_mul_f32 v[4:5], v[6:7], v[4:5]
	s_nop 0
	v_cvt_pk_bf16_f32 v239, v4, v5
	s_nop 1
	v_permlane16_swap_b32_e32 v232, v234
	v_permlane16_swap_b32_e32 v233, v235
	v_permlane16_swap_b32_e32 v236, v238
	v_permlane16_swap_b32_e32 v237, v239
	v_lshl_add_u64 v[240:241], v[28:29], 0, v[244:245]
	global_store_dwordx4 v[240:241], v[232:235], off sc1
	global_store_dwordx4 v[240:241], v[236:239], off offset:64 sc1
	s_barrier
	s_cbranch_vccz .LBB0_371

.LBB0_362:
	s_or_b64 exec, exec, s[38:39]
	s_waitcnt vmcnt(0)
	s_barrier
	s_cmp_lt_i32 s99, 0
	s_cbranch_scc1 .Lp5_nosig
	s_and_saveexec_b64 s[100:101], s[2:3]
	s_cbranch_execz .Lp5_sig_done
	s_lshl_b32 s0, s99, 6
	s_add_u32 s0, s11, s0
	s_addc_u32 s1, s33, 0
	s_add_u32 s0, s0, 0x1000
	s_addc_u32 s1, s1, 0
	global_atomic_add v131, v153, s[0:1]
.Lp5_sig_done:
	s_or_b64 exec, exec, s[100:101]
.Lp5_nosig:
	s_mov_b32 s99, s34
	s_load_dword s0, s[16:17], 0x0
	s_waitcnt lgkmcnt(0)
	s_add_i32 s54, s0, s54
	s_cmpk_gt_i32 s54, 0x57f
	s_cselect_b64 s[38:39], -1, 0
	s_cmpk_lt_i32 s54, 0x580
	s_cselect_b64 s[0:1], -1, 0
	s_and_b64 s[0:1], s[2:3], s[0:1]
	s_and_saveexec_b64 s[40:41], s[0:1]
	s_cbranch_execz .LBB0_341
	s_mul_hi_i32 s0, s54, 0x2e8ba2e9
	s_lshr_b32 s1, s0, 31
	s_lshr_b32 s0, s0, 2
	s_add_i32 s0, s0, s1
	s_lshl_b32 s0, s0, 4
	s_ashr_i32 s1, s0, 31
	s_lshl_b64 s[0:1], s[0:1], 2
	s_add_u32 s46, s11, s0
	s_addc_u32 s47, s33, s1
	s_mov_b32 s35, 0x400001
	s_branch .LBB0_365

.LBB0_371:
	s_cmp_gt_i32 s86, 6
	s_cselect_b64 s[2:3], -1, 0
	s_and_b64 s[0:1], s[8:9], s[2:3]
	s_andn2_b64 vcc, exec, s[0:1]
	s_cbranch_vccnz .LBB0_391
	s_waitcnt vmcnt(0) lgkmcnt(0)
	s_add_u32 s6, s96, 0x188
	s_addc_u32 s7, s97, 0
	v_cmp_eq_u32_e32 vcc, 0, v0
	s_waitcnt lgkmcnt(0)
	s_barrier
	s_and_saveexec_b64 s[4:5], vcc
	s_cbranch_execz .LBB0_390
	s_cmp_lt_i32 s99, 0
	s_cbranch_scc1 .Lp6_poll_setup
	s_lshl_b32 s0, s99, 6
	s_add_u32 s0, s94, s0
	s_addc_u32 s1, s95, 0
	s_add_u32 s0, s0, 0x3000
	s_addc_u32 s1, s1, 0
	v_mov_b32_e32 v1, 0
	v_mov_b32_e32 v2, 1
	global_atomic_add v1, v2, s[0:1]
.Lp6_poll_setup:
	s_ashr_i32 s0, s10, 2
	s_lshl_b32 s0, s0, 6
	s_add_u32 s6, s94, s0
	s_addc_u32 s7, s95, 0
	s_add_u32 s6, s6, 0x3000
	s_addc_u32 s7, s7, 0
	s_mov_b32 s11, 0x400001
	v_mov_b32_e32 v1, 0
.Lp6_flag_poll:
	global_load_dword v2, v1, s[6:7] sc1
	s_waitcnt vmcnt(0)
	v_cmp_lt_u32_e32 vcc, 21, v2
	s_cbranch_vccnz .LBB0_389
	s_sleep 8
	s_add_i32 s11, s11, -1
	s_cmp_lg_u32 s11, 0
	s_cbranch_scc1 .Lp6_flag_poll
